# scan: streaming (nt) policy on the 2-byte output stores (yl/caf/cab, sums)
# speedup vs baseline: 1.0078x; 1.0078x over previous
; __device__ __forceinline__ bf16_t f2bf(float f) { unsigned u = __float_as_uint(f); u += 0x7FFFu + ((u >> 16) & 1u); return (bf16_t)(u >> 16); }
; template <int DIR>
; __device__ __forceinline__ void scan_dir(PP p, const bf16_t* xs, const ScanW& w, ScanW& wn, int ndir, int nct, bool do_next, int n, int ct, int l31, int hl, int id, int rowbase, bool latent, float (&hf)[2][16]) {
;     ...
;     float Sin[8], Pin[8]; float Sx = 0.f, Px = 1.f;
; #pragma unroll
;     for (int kk = 0; kk < 8; ++kk) {
;         const int k = DIR ? 7 - kk : kk;
;         const float A0 = hl ? Ap[k] : Ao[k], H0 = hl ? Hp[k] : Ho[k], A1 = hl ? Ao[k] : Ap[k], H1 = hl ? Ho[k] : Hp[k];
;         float s0, p0, s1, p1;
;         if (DIR == 0) { s0 = Sx; p0 = Px; Sx = A0 * Sx + H0; Px *= A0; s1 = Sx; p1 = Px; Sx = A1 * Sx + H1; Px *= A1; }
;         else          { s1 = Sx; p1 = Px; Sx = A1 * Sx + H1; Px *= A1; s0 = Sx; p0 = Px; Sx = A0 * Sx + H0; Px *= A0; }
;         Sin[k] = hl ? s1 : s0; Pin[k] = hl ? p1 : p0;
;     }
;     asm volatile("" ::: "memory");
;     if (do_next) scan_loadw(p, ndir, n, nct, l31, hl, wn);
;     bf16_t* yl = (bf16_t*)(p->ws + WS_YL) + (size_t)rowbase * 512; bf16_t* caf = (bf16_t*)(p->ws + WS_CAF) + (size_t)rowbase * 512; bf16_t* cab = (bf16_t*)(p->ws + WS_CAB) + (size_t)rowbase * 512;
;     unsigned lo = (unsigned)ch; asm volatile("" : "+v"(lo));
; #pragma unroll
;     for (int k = 0; k < 8; ++k) {
;         const int rt = k >> 2, g = k & 3;
;         float h = Sin[k], P = Pin[k];
; #pragma unroll
;         for (int jj = 0; jj < 4; ++jj) {
;             const int j = DIR ? 3 - jj : jj, idx = 4 * g + j;
;             h = a[rt][idx] * h + u[rt][idx]; P *= a[rt][idx];
;             const int token = 32 * rt + 8 * g + 4 * hl + j;
;             const unsigned o = lo + (unsigned)token * 512u;
;             if (DIR == 0) { hf[rt][idx] = h; if (latent) caf[o] = f2bf(P); }
;             else if (latent) { yl[o] = f2bf(hf[rt][idx] + h); cab[o] = f2bf(P); }
;         }
.LBB0_380:
	s_waitcnt lgkmcnt(14)
	v_cndmask_b32_e64 v0, v36, 1.0, s[6:7]
	v_mov_b32_e32 v238, v66
	s_and_b64 vcc, exec, s[4:5]
	v_mul_f32_e32 v9, v50, v0
	s_cbranch_vccnz .LBB0_382
	v_add_u32_e32 v0, v238, v153
	v_bfe_u32 v10, v9, 16, 1
	v_add3_u32 v12, v9, v10, s77
	v_lshl_add_u64 v[10:11], v[0:1], 1, s[30:31]
	global_store_short_d16_hi v[10:11], v12, off nt
.LBB0_382:
	s_and_b64 vcc, exec, s[4:5]
	v_mul_f32_e32 v39, v52, v9
	s_cbranch_vccnz .LBB0_384
	v_or_b32_e32 v0, 0x200, v153
	v_add_u32_e32 v0, v0, v238
	v_bfe_u32 v9, v39, 16, 1
	v_add3_u32 v9, v39, v9, s77
	v_lshl_add_u64 v[10:11], v[0:1], 1, s[30:31]
	global_store_short_d16_hi v[10:11], v9, off nt

; __device__ __forceinline__ bf16_t f2bf(float f) { unsigned u = __float_as_uint(f); u += 0x7FFFu + ((u >> 16) & 1u); return (bf16_t)(u >> 16); }
; template <int DIR>
; __device__ __forceinline__ void scan_dir(PP p, const bf16_t* xs, const ScanW& w, ScanW& wn, int ndir, int nct, bool do_next, int n, int ct, int l31, int hl, int id, int rowbase, bool latent, float (&hf)[2][16]) {
;     ...
;     for (int k = 0; k < 8; ++k) {
;         const int rt = k >> 2, g = k & 3;
;         float h = Sin[k], P = Pin[k];
; #pragma unroll
;         for (int jj = 0; jj < 4; ++jj) {
;             const int j = DIR ? 3 - jj : jj, idx = 4 * g + j;
;             h = a[rt][idx] * h + u[rt][idx]; P *= a[rt][idx];
;             const int token = 32 * rt + 8 * g + 4 * hl + j;
;             const unsigned o = lo + (unsigned)token * 512u;
;             if (DIR == 0) { hf[rt][idx] = h; if (latent) caf[o] = f2bf(P); }
;             else if (latent) { yl[o] = f2bf(hf[rt][idx] + h); cab[o] = f2bf(P); }
;         }
.LBB0_386:
	s_andn2_b64 vcc, exec, s[48:49]
	s_cbranch_vccnz .LBB0_388
	v_mul_f32_e32 v39, v51, v39
	v_or_b32_e32 v0, 0x400, v153
	v_add_u32_e32 v0, v0, v238
	v_bfe_u32 v40, v39, 16, 1
	v_add3_u32 v42, v39, v40, s77
	v_lshl_add_u64 v[40:41], v[0:1], 1, s[30:31]
	v_mul_f32_e32 v39, v54, v39
	v_or_b32_e32 v0, 0x600, v153
	global_store_short_d16_hi v[40:41], v42, off nt
	v_add_u32_e32 v0, v0, v238
	v_bfe_u32 v40, v39, 16, 1
	v_add3_u32 v39, v39, v40, s77
	v_lshl_add_u64 v[40:41], v[0:1], 1, s[30:31]
	global_store_short_d16_hi v[40:41], v39, off nt
.LBB0_388:
	v_mul_f32_e32 v0, v35, v36
	s_waitcnt lgkmcnt(13)
	v_cndmask_b32_e64 v39, v155, v154, s[6:7]
	v_mul_f32_e32 v156, v0, v39
	v_cndmask_b32_e64 v0, v156, v0, s[6:7]
	s_and_b64 vcc, exec, s[4:5]
	v_mul_f32_e32 v40, v53, v0
	s_cbranch_vccnz .LBB0_390
	v_add_u32_e32 v0, v238, v157
	v_bfe_u32 v41, v40, 16, 1
	v_add3_u32 v41, v40, v41, s77
	v_lshl_add_u64 v[42:43], v[0:1], 1, s[30:31]
	global_store_short_d16_hi v[42:43], v41, off nt
.LBB0_390:
	s_and_b64 vcc, exec, s[4:5]
	v_mul_f32_e32 v159, v55, v40
	s_cbranch_vccnz .LBB0_392
	v_or_b32_e32 v0, 0x1200, v153
	v_add_u32_e32 v0, v0, v238
	v_bfe_u32 v40, v159, 16, 1
	v_add3_u32 v42, v159, v40, s77
	v_lshl_add_u64 v[40:41], v[0:1], 1, s[30:31]
	global_store_short_d16_hi v[40:41], v42, off nt

; __device__ __forceinline__ bf16_t f2bf(float f) { unsigned u = __float_as_uint(f); u += 0x7FFFu + ((u >> 16) & 1u); return (bf16_t)(u >> 16); }
; template <int DIR>
; __device__ __forceinline__ void scan_dir(PP p, const bf16_t* xs, const ScanW& w, ScanW& wn, int ndir, int nct, bool do_next, int n, int ct, int l31, int hl, int id, int rowbase, bool latent, float (&hf)[2][16]) {
;     ...
;     for (int k = 0; k < 8; ++k) {
;         const int rt = k >> 2, g = k & 3;
;         float h = Sin[k], P = Pin[k];
; #pragma unroll
;         for (int jj = 0; jj < 4; ++jj) {
;             const int j = DIR ? 3 - jj : jj, idx = 4 * g + j;
;             h = a[rt][idx] * h + u[rt][idx]; P *= a[rt][idx];
;             const int token = 32 * rt + 8 * g + 4 * hl + j;
;             const unsigned o = lo + (unsigned)token * 512u;
;             if (DIR == 0) { hf[rt][idx] = h; if (latent) caf[o] = f2bf(P); }
;             else if (latent) { yl[o] = f2bf(hf[rt][idx] + h); cab[o] = f2bf(P); }
;         }
.LBB0_394:
	s_andn2_b64 vcc, exec, s[48:49]
	s_cbranch_vccnz .LBB0_396
	v_mul_f32_e32 v4, v67, v159
	v_or_b32_e32 v0, 0x1400, v153
	v_add_u32_e32 v0, v0, v238
	v_bfe_u32 v2, v4, 16, 1
	v_add3_u32 v5, v4, v2, s77
	v_lshl_add_u64 v[2:3], v[0:1], 1, s[30:31]
	global_store_short_d16_hi v[2:3], v5, off nt
	v_mul_f32_e32 v2, v69, v4
	v_add_u32_e32 v0, v160, v238
	v_bfe_u32 v3, v2, 16, 1
	v_add3_u32 v4, v2, v3, s77
	v_lshl_add_u64 v[2:3], v[0:1], 1, s[30:31]
	global_store_short_d16_hi v[2:3], v4, off nt
	v_mov_b64_e32 v[2:3], v[34:35]
	v_mov_b64_e32 v[4:5], v[36:37]
	v_mov_b64_e32 v[6:7], v[38:39]
	v_mov_b64_e32 v[8:9], v[40:41]
	v_mov_b64_e32 v[12:13], v[44:45]
	v_mov_b64_e32 v[14:15], v[46:47]
	v_mov_b64_e32 v[16:17], v[48:49]
	v_mov_b64_e32 v[18:19], v[50:51]
	v_mov_b64_e32 v[20:21], v[52:53]
	v_mov_b64_e32 v[22:23], v[54:55]
	v_mov_b64_e32 v[24:25], v[56:57]
	v_mov_b64_e32 v[26:27], v[58:59]
	v_mov_b64_e32 v[28:29], v[60:61]
	v_mov_b64_e32 v[30:31], v[62:63]
	v_mov_b64_e32 v[32:33], v[64:65]
	v_mov_b64_e32 v[10:11], v[42:43]
.LBB0_396:
	v_cndmask_b32_e64 v11, v154, v155, s[6:7]
	v_mul_f32_e32 v0, v11, v156
	s_waitcnt lgkmcnt(11)
	v_cndmask_b32_e64 v10, v254, v253, s[6:7]
	v_mul_f32_e32 v69, v0, v10
	v_cndmask_b32_e64 v0, v69, v0, s[6:7]
	s_and_b64 vcc, exec, s[4:5]
	v_mul_f32_e32 v12, v68, v0
	s_cbranch_vccnz .LBB0_398
	v_add_u32_e32 v0, v238, v161
	v_bfe_u32 v34, v12, 16, 1
	v_add3_u32 v36, v12, v34, s77
	v_lshl_add_u64 v[34:35], v[0:1], 1, s[30:31]
	global_store_short_d16_hi v[34:35], v36, off nt
.LBB0_398:
	s_and_b64 vcc, exec, s[4:5]
	v_mul_f32_e32 v76, v71, v12
	s_cbranch_vccnz .LBB0_400
	v_add_u32_e32 v0, v162, v238
	v_bfe_u32 v12, v76, 16, 1
	v_add3_u32 v12, v76, v12, s77
	v_lshl_add_u64 v[34:35], v[0:1], 1, s[30:31]
	global_store_short_d16_hi v[34:35], v12, off nt

; __device__ __forceinline__ bf16_t f2bf(float f) { unsigned u = __float_as_uint(f); u += 0x7FFFu + ((u >> 16) & 1u); return (bf16_t)(u >> 16); }
; template <int DIR>
; __device__ __forceinline__ void scan_dir(PP p, const bf16_t* xs, const ScanW& w, ScanW& wn, int ndir, int nct, bool do_next, int n, int ct, int l31, int hl, int id, int rowbase, bool latent, float (&hf)[2][16]) {
;     ...
;     for (int k = 0; k < 8; ++k) {
;         const int rt = k >> 2, g = k & 3;
;         float h = Sin[k], P = Pin[k];
; #pragma unroll
;         for (int jj = 0; jj < 4; ++jj) {
;             const int j = DIR ? 3 - jj : jj, idx = 4 * g + j;
;             h = a[rt][idx] * h + u[rt][idx]; P *= a[rt][idx];
;             const int token = 32 * rt + 8 * g + 4 * hl + j;
;             const unsigned o = lo + (unsigned)token * 512u;
;             if (DIR == 0) { hf[rt][idx] = h; if (latent) caf[o] = f2bf(P); }
;             else if (latent) { yl[o] = f2bf(hf[rt][idx] + h); cab[o] = f2bf(P); }
;         }
.LBB0_402:
	s_andn2_b64 vcc, exec, s[48:49]
	s_cbranch_vccnz .LBB0_404
	v_mul_f32_e32 v4, v70, v76
	v_add_u32_e32 v0, v163, v238
	v_bfe_u32 v2, v4, 16, 1
	v_add3_u32 v5, v4, v2, s77
	v_lshl_add_u64 v[2:3], v[0:1], 1, s[30:31]
	global_store_short_d16_hi v[2:3], v5, off nt
	v_mul_f32_e32 v2, v75, v4
	v_add_u32_e32 v0, v164, v238
	v_bfe_u32 v3, v2, 16, 1
	v_add3_u32 v4, v2, v3, s77
	v_lshl_add_u64 v[2:3], v[0:1], 1, s[30:31]
	global_store_short_d16_hi v[2:3], v4, off nt
	v_mov_b64_e32 v[2:3], v[34:35]
	v_mov_b64_e32 v[4:5], v[36:37]
	v_mov_b64_e32 v[6:7], v[38:39]
	v_mov_b64_e32 v[8:9], v[40:41]
	v_mov_b64_e32 v[10:11], v[42:43]
	v_mov_b64_e32 v[12:13], v[44:45]
	v_mov_b64_e32 v[16:17], v[48:49]
	v_mov_b64_e32 v[18:19], v[50:51]
	v_mov_b64_e32 v[20:21], v[52:53]
	v_mov_b64_e32 v[22:23], v[54:55]
	v_mov_b64_e32 v[24:25], v[56:57]
	v_mov_b64_e32 v[26:27], v[58:59]
	v_mov_b64_e32 v[28:29], v[60:61]
	v_mov_b64_e32 v[30:31], v[62:63]
	v_mov_b64_e32 v[32:33], v[64:65]
	v_mov_b64_e32 v[14:15], v[46:47]
.LBB0_404:
	v_cndmask_b32_e64 v15, v253, v254, s[6:7]
	v_mul_f32_e32 v0, v15, v69
	s_waitcnt lgkmcnt(9)
	v_cndmask_b32_e64 v14, v250, v249, s[6:7]
	v_mul_f32_e32 v68, v0, v14
	v_cndmask_b32_e64 v0, v68, v0, s[6:7]
	s_and_b64 vcc, exec, s[4:5]
	v_mul_f32_e32 v16, v72, v0
	s_cbranch_vccnz .LBB0_406
	v_add_u32_e32 v0, v238, v165
	v_bfe_u32 v34, v16, 16, 1
	v_add3_u32 v36, v16, v34, s77
	v_lshl_add_u64 v[34:35], v[0:1], 1, s[30:31]
	global_store_short_d16_hi v[34:35], v36, off nt
.LBB0_406:
	s_and_b64 vcc, exec, s[4:5]
	v_mul_f32_e32 v69, v78, v16
	s_cbranch_vccnz .LBB0_408
	v_add_u32_e32 v0, v166, v238
	v_bfe_u32 v16, v69, 16, 1
	v_add3_u32 v16, v69, v16, s77
	v_lshl_add_u64 v[34:35], v[0:1], 1, s[30:31]
	global_store_short_d16_hi v[34:35], v16, off nt

; __device__ __forceinline__ bf16_t f2bf(float f) { unsigned u = __float_as_uint(f); u += 0x7FFFu + ((u >> 16) & 1u); return (bf16_t)(u >> 16); }
; template <int DIR>
; __device__ __forceinline__ void scan_dir(PP p, const bf16_t* xs, const ScanW& w, ScanW& wn, int ndir, int nct, bool do_next, int n, int ct, int l31, int hl, int id, int rowbase, bool latent, float (&hf)[2][16]) {
;     ...
;     for (int k = 0; k < 8; ++k) {
;         const int rt = k >> 2, g = k & 3;
;         float h = Sin[k], P = Pin[k];
; #pragma unroll
;         for (int jj = 0; jj < 4; ++jj) {
;             const int j = DIR ? 3 - jj : jj, idx = 4 * g + j;
;             h = a[rt][idx] * h + u[rt][idx]; P *= a[rt][idx];
;             const int token = 32 * rt + 8 * g + 4 * hl + j;
;             const unsigned o = lo + (unsigned)token * 512u;
;             if (DIR == 0) { hf[rt][idx] = h; if (latent) caf[o] = f2bf(P); }
;             else if (latent) { yl[o] = f2bf(hf[rt][idx] + h); cab[o] = f2bf(P); }
;         }
.LBB0_410:
	s_andn2_b64 vcc, exec, s[48:49]
	s_cbranch_vccnz .LBB0_412
	v_mul_f32_e32 v4, v77, v69
	v_add_u32_e32 v0, v167, v238
	v_bfe_u32 v2, v4, 16, 1
	v_add3_u32 v5, v4, v2, s77
	v_lshl_add_u64 v[2:3], v[0:1], 1, s[30:31]
	global_store_short_d16_hi v[2:3], v5, off nt
	v_mul_f32_e32 v2, v79, v4
	v_add_u32_e32 v0, v168, v238
	v_bfe_u32 v3, v2, 16, 1
	v_add3_u32 v4, v2, v3, s77
	v_lshl_add_u64 v[2:3], v[0:1], 1, s[30:31]
	global_store_short_d16_hi v[2:3], v4, off nt
	v_mov_b64_e32 v[2:3], v[34:35]
	v_mov_b64_e32 v[4:5], v[36:37]
	v_mov_b64_e32 v[6:7], v[38:39]
	v_mov_b64_e32 v[8:9], v[40:41]
	v_mov_b64_e32 v[10:11], v[42:43]
	v_mov_b64_e32 v[12:13], v[44:45]
	v_mov_b64_e32 v[14:15], v[46:47]
	v_mov_b64_e32 v[16:17], v[48:49]
	v_mov_b64_e32 v[20:21], v[52:53]
	v_mov_b64_e32 v[22:23], v[54:55]
	v_mov_b64_e32 v[24:25], v[56:57]
	v_mov_b64_e32 v[26:27], v[58:59]
	v_mov_b64_e32 v[28:29], v[60:61]
	v_mov_b64_e32 v[30:31], v[62:63]
	v_mov_b64_e32 v[32:33], v[64:65]
	v_mov_b64_e32 v[18:19], v[50:51]
.LBB0_412:
	v_cndmask_b32_e64 v19, v249, v250, s[6:7]
	v_mul_f32_e32 v0, v19, v68
	s_waitcnt lgkmcnt(7)
	v_cndmask_b32_e64 v18, v246, v245, s[6:7]
	v_mul_f32_e32 v68, v0, v18
	v_cndmask_b32_e64 v0, v68, v0, s[6:7]
	s_and_b64 vcc, exec, s[4:5]
	v_mul_f32_e32 v20, v80, v0
	s_cbranch_vccnz .LBB0_414
	v_add_u32_e32 v0, v238, v169
	v_bfe_u32 v34, v20, 16, 1
	v_add3_u32 v36, v20, v34, s77
	v_lshl_add_u64 v[34:35], v[0:1], 1, s[30:31]
	global_store_short_d16_hi v[34:35], v36, off nt
.LBB0_414:
	s_and_b64 vcc, exec, s[4:5]
	v_mul_f32_e32 v69, v146, v20
	s_cbranch_vccnz .LBB0_416
	v_add_u32_e32 v0, v170, v238
	v_bfe_u32 v20, v69, 16, 1
	v_add3_u32 v20, v69, v20, s77
	v_lshl_add_u64 v[34:35], v[0:1], 1, s[30:31]
	global_store_short_d16_hi v[34:35], v20, off nt

; __device__ __forceinline__ bf16_t f2bf(float f) { unsigned u = __float_as_uint(f); u += 0x7FFFu + ((u >> 16) & 1u); return (bf16_t)(u >> 16); }
; template <int DIR>
; __device__ __forceinline__ void scan_dir(PP p, const bf16_t* xs, const ScanW& w, ScanW& wn, int ndir, int nct, bool do_next, int n, int ct, int l31, int hl, int id, int rowbase, bool latent, float (&hf)[2][16]) {
;     ...
;     for (int k = 0; k < 8; ++k) {
;         const int rt = k >> 2, g = k & 3;
;         float h = Sin[k], P = Pin[k];
; #pragma unroll
;         for (int jj = 0; jj < 4; ++jj) {
;             const int j = DIR ? 3 - jj : jj, idx = 4 * g + j;
;             h = a[rt][idx] * h + u[rt][idx]; P *= a[rt][idx];
;             const int token = 32 * rt + 8 * g + 4 * hl + j;
;             const unsigned o = lo + (unsigned)token * 512u;
;             if (DIR == 0) { hf[rt][idx] = h; if (latent) caf[o] = f2bf(P); }
;             else if (latent) { yl[o] = f2bf(hf[rt][idx] + h); cab[o] = f2bf(P); }
;         }
.LBB0_418:
	s_andn2_b64 vcc, exec, s[48:49]
	s_cbranch_vccnz .LBB0_420
	v_mul_f32_e32 v4, v81, v69
	v_add_u32_e32 v0, v171, v238
	v_bfe_u32 v2, v4, 16, 1
	v_add3_u32 v5, v4, v2, s77
	v_lshl_add_u64 v[2:3], v[0:1], 1, s[30:31]
	global_store_short_d16_hi v[2:3], v5, off nt
	v_mul_f32_e32 v2, v198, v4
	v_add_u32_e32 v0, v172, v238
	v_bfe_u32 v3, v2, 16, 1
	v_add3_u32 v4, v2, v3, s77
	v_lshl_add_u64 v[2:3], v[0:1], 1, s[30:31]
	global_store_short_d16_hi v[2:3], v4, off nt
	v_mov_b64_e32 v[2:3], v[34:35]
	v_mov_b64_e32 v[4:5], v[36:37]
	v_mov_b64_e32 v[6:7], v[38:39]
	v_mov_b64_e32 v[8:9], v[40:41]
	v_mov_b64_e32 v[10:11], v[42:43]
	v_mov_b64_e32 v[12:13], v[44:45]
	v_mov_b64_e32 v[14:15], v[46:47]
	v_mov_b64_e32 v[16:17], v[48:49]
	v_mov_b64_e32 v[18:19], v[50:51]
	v_mov_b64_e32 v[20:21], v[52:53]
	v_mov_b64_e32 v[24:25], v[56:57]
	v_mov_b64_e32 v[26:27], v[58:59]
	v_mov_b64_e32 v[28:29], v[60:61]
	v_mov_b64_e32 v[30:31], v[62:63]
	v_mov_b64_e32 v[32:33], v[64:65]
	v_mov_b64_e32 v[22:23], v[54:55]
.LBB0_420:
	v_cndmask_b32_e64 v23, v245, v246, s[6:7]
	v_mul_f32_e32 v0, v23, v68
	s_waitcnt lgkmcnt(5)
	v_cndmask_b32_e64 v22, v242, v241, s[6:7]
	v_mul_f32_e32 v68, v0, v22
	v_cndmask_b32_e64 v0, v68, v0, s[6:7]
	s_and_b64 vcc, exec, s[4:5]
	v_mul_f32_e32 v24, v147, v0
	s_cbranch_vccnz .LBB0_422
	v_add_u32_e32 v0, v238, v173
	v_bfe_u32 v34, v24, 16, 1
	v_add3_u32 v36, v24, v34, s77
	v_lshl_add_u64 v[34:35], v[0:1], 1, s[30:31]
	global_store_short_d16_hi v[34:35], v36, off nt
.LBB0_422:
	s_and_b64 vcc, exec, s[4:5]
	v_mul_f32_e32 v69, v201, v24
	s_cbranch_vccnz .LBB0_424
	v_add_u32_e32 v0, v238, v174
	v_bfe_u32 v24, v69, 16, 1
	v_add3_u32 v24, v69, v24, s77
	v_lshl_add_u64 v[34:35], v[0:1], 1, s[30:31]
	global_store_short_d16_hi v[34:35], v24, off nt

; __device__ __forceinline__ bf16_t f2bf(float f) { unsigned u = __float_as_uint(f); u += 0x7FFFu + ((u >> 16) & 1u); return (bf16_t)(u >> 16); }
; template <int DIR>
; __device__ __forceinline__ void scan_dir(PP p, const bf16_t* xs, const ScanW& w, ScanW& wn, int ndir, int nct, bool do_next, int n, int ct, int l31, int hl, int id, int rowbase, bool latent, float (&hf)[2][16]) {
;     ...
;     for (int k = 0; k < 8; ++k) {
;         const int rt = k >> 2, g = k & 3;
;         float h = Sin[k], P = Pin[k];
; #pragma unroll
;         for (int jj = 0; jj < 4; ++jj) {
;             const int j = DIR ? 3 - jj : jj, idx = 4 * g + j;
;             h = a[rt][idx] * h + u[rt][idx]; P *= a[rt][idx];
;             const int token = 32 * rt + 8 * g + 4 * hl + j;
;             const unsigned o = lo + (unsigned)token * 512u;
;             if (DIR == 0) { hf[rt][idx] = h; if (latent) caf[o] = f2bf(P); }
;             else if (latent) { yl[o] = f2bf(hf[rt][idx] + h); cab[o] = f2bf(P); }
;         }
.LBB0_426:
	s_andn2_b64 vcc, exec, s[48:49]
	s_cbranch_vccnz .LBB0_428
	v_mul_f32_e32 v4, v200, v69
	v_add_u32_e32 v0, v238, v175
	v_bfe_u32 v2, v4, 16, 1
	v_add3_u32 v5, v4, v2, s77
	v_lshl_add_u64 v[2:3], v[0:1], 1, s[30:31]
	global_store_short_d16_hi v[2:3], v5, off nt
	v_mul_f32_e32 v2, v207, v4
	v_add_u32_e32 v0, v238, v176
	v_bfe_u32 v3, v2, 16, 1
	v_add3_u32 v4, v2, v3, s77
	v_lshl_add_u64 v[2:3], v[0:1], 1, s[30:31]
	global_store_short_d16_hi v[2:3], v4, off nt
	v_mov_b64_e32 v[2:3], v[34:35]
	v_mov_b64_e32 v[4:5], v[36:37]
	v_mov_b64_e32 v[6:7], v[38:39]
	v_mov_b64_e32 v[8:9], v[40:41]
	v_mov_b64_e32 v[10:11], v[42:43]
	v_mov_b64_e32 v[12:13], v[44:45]
	v_mov_b64_e32 v[14:15], v[46:47]
	v_mov_b64_e32 v[16:17], v[48:49]
	v_mov_b64_e32 v[18:19], v[50:51]
	v_mov_b64_e32 v[20:21], v[52:53]
	v_mov_b64_e32 v[22:23], v[54:55]
	v_mov_b64_e32 v[24:25], v[56:57]
	v_mov_b64_e32 v[28:29], v[60:61]
	v_mov_b64_e32 v[30:31], v[62:63]
	v_mov_b64_e32 v[32:33], v[64:65]
	v_mov_b64_e32 v[26:27], v[58:59]
.LBB0_428:
	v_cndmask_b32_e64 v27, v241, v242, s[6:7]
	v_mul_f32_e32 v0, v27, v68
	s_waitcnt lgkmcnt(3)
	v_cndmask_b32_e64 v26, v237, v236, s[6:7]
	v_mul_f32_e32 v69, v0, v26
	v_cndmask_b32_e64 v0, v69, v0, s[6:7]
	s_and_b64 vcc, exec, s[4:5]
	v_mul_f32_e32 v28, v203, v0
	s_cbranch_vccnz .LBB0_430
	v_add_u32_e32 v0, v238, v177
	v_bfe_u32 v34, v28, 16, 1
	v_add3_u32 v36, v28, v34, s77
	v_lshl_add_u64 v[34:35], v[0:1], 1, s[30:31]
	global_store_short_d16_hi v[34:35], v36, off nt
.LBB0_430:
	s_and_b64 vcc, exec, s[4:5]
	v_mul_f32_e32 v70, v210, v28
	s_cbranch_vccnz .LBB0_432
	v_add_u32_e32 v0, v238, v178
	v_bfe_u32 v28, v70, 16, 1
	v_add3_u32 v28, v70, v28, s77
	v_lshl_add_u64 v[34:35], v[0:1], 1, s[30:31]
	global_store_short_d16_hi v[34:35], v28, off nt

; __device__ __forceinline__ bf16_t f2bf(float f) { unsigned u = __float_as_uint(f); u += 0x7FFFu + ((u >> 16) & 1u); return (bf16_t)(u >> 16); }
; template <int DIR>
; __device__ __forceinline__ void scan_dir(PP p, const bf16_t* xs, const ScanW& w, ScanW& wn, int ndir, int nct, bool do_next, int n, int ct, int l31, int hl, int id, int rowbase, bool latent, float (&hf)[2][16]) {
;     ...
;     for (int k = 0; k < 8; ++k) {
;         const int rt = k >> 2, g = k & 3;
;         float h = Sin[k], P = Pin[k];
; #pragma unroll
;         for (int jj = 0; jj < 4; ++jj) {
;             const int j = DIR ? 3 - jj : jj, idx = 4 * g + j;
;             h = a[rt][idx] * h + u[rt][idx]; P *= a[rt][idx];
;             const int token = 32 * rt + 8 * g + 4 * hl + j;
;             const unsigned o = lo + (unsigned)token * 512u;
;             if (DIR == 0) { hf[rt][idx] = h; if (latent) caf[o] = f2bf(P); }
;             else if (latent) { yl[o] = f2bf(hf[rt][idx] + h); cab[o] = f2bf(P); }
;         }
.LBB0_434:
	s_andn2_b64 vcc, exec, s[48:49]
	s_cbranch_vccnz .LBB0_436
	v_mul_f32_e32 v4, v208, v70
	v_add_u32_e32 v0, v238, v179
	v_bfe_u32 v2, v4, 16, 1
	v_add3_u32 v5, v4, v2, s77
	v_lshl_add_u64 v[2:3], v[0:1], 1, s[30:31]
	global_store_short_d16_hi v[2:3], v5, off nt
	v_mul_f32_e32 v2, v218, v4
	v_add_u32_e32 v0, v238, v180
	v_bfe_u32 v3, v2, 16, 1
	v_add3_u32 v4, v2, v3, s77
	v_lshl_add_u64 v[2:3], v[0:1], 1, s[30:31]
	global_store_short_d16_hi v[2:3], v4, off nt
	v_mov_b64_e32 v[2:3], v[34:35]
	v_mov_b64_e32 v[4:5], v[36:37]
	v_mov_b64_e32 v[6:7], v[38:39]
	v_mov_b64_e32 v[8:9], v[40:41]
	v_mov_b64_e32 v[10:11], v[42:43]
	v_mov_b64_e32 v[12:13], v[44:45]
	v_mov_b64_e32 v[14:15], v[46:47]
	v_mov_b64_e32 v[16:17], v[48:49]
	v_mov_b64_e32 v[18:19], v[50:51]
	v_mov_b64_e32 v[20:21], v[52:53]
	v_mov_b64_e32 v[22:23], v[54:55]
	v_mov_b64_e32 v[24:25], v[56:57]
	v_mov_b64_e32 v[26:27], v[58:59]
	v_mov_b64_e32 v[28:29], v[60:61]
	v_mov_b64_e32 v[32:33], v[64:65]
	v_mov_b64_e32 v[30:31], v[62:63]
.LBB0_436:
	v_cndmask_b32_e64 v31, v236, v237, s[6:7]
	v_mul_f32_e32 v0, v31, v69
	s_waitcnt lgkmcnt(1)
	v_cndmask_b32_e64 v30, v232, v231, s[6:7]
	v_mul_f32_e32 v67, v0, v30
	v_cndmask_b32_e64 v0, v67, v0, s[6:7]
	s_and_b64 vcc, exec, s[4:5]
	v_mul_f32_e32 v32, v213, v0
	s_cbranch_vccnz .LBB0_438
	v_add_u32_e32 v0, v238, v181
	v_bfe_u32 v34, v32, 16, 1
	v_add3_u32 v36, v32, v34, s77
	v_lshl_add_u64 v[34:35], v[0:1], 1, s[30:31]
	global_store_short_d16_hi v[34:35], v36, off nt
.LBB0_438:
	s_and_b64 vcc, exec, s[4:5]
	v_mul_f32_e32 v69, v220, v32
	s_cbranch_vccnz .LBB0_440
	v_add_u32_e32 v0, v238, v182
	v_bfe_u32 v32, v69, 16, 1
	v_add3_u32 v32, v69, v32, s77
	v_lshl_add_u64 v[34:35], v[0:1], 1, s[30:31]
	global_store_short_d16_hi v[34:35], v32, off nt

; template <int DIR>
; __device__ __forceinline__ void scan_dir(PP p, const bf16_t* xs, const ScanW& w, ScanW& wn, int ndir, int nct, bool do_next, int n, int ct, int l31, int hl, int id, int rowbase, bool latent, float (&hf)[2][16]) {
;     ...
;         const float A0 = hl ? Ap[k] : Ao[k], H0 = hl ? Hp[k] : Ho[k], A1 = hl ? Ao[k] : Ap[k], H1 = hl ? Ho[k] : Hp[k];
;         float s0, p0, s1, p1;
;         if (DIR == 0) { s0 = Sx; p0 = Px; Sx = A0 * Sx + H0; Px *= A0; s1 = Sx; p1 = Px; Sx = A1 * Sx + H1; Px *= A1; }
;         else          { s1 = Sx; p1 = Px; Sx = A1 * Sx + H1; Px *= A1; s0 = Sx; p0 = Px; Sx = A0 * Sx + H0; Px *= A0; }
;         Sin[k] = hl ? s1 : s0; Pin[k] = hl ? p1 : p0;
;     ...
;     if (hl == 0) {
;         float* sumb = (float*)(p->ws + WS_SUM);
;         sumb[((size_t)(DIR * NCHUNK + id) * 2 + 0) * 512 + ch] = Px;
;         sumb[((size_t)(DIR * NCHUNK + id) * 2 + 1) * 512 + ch] = Sx;
;     }
.LBB0_443:
	v_cndmask_b32_e64 v0, v231, v232, s[6:7]
	v_cndmask_b32_e64 v36, v230, v233, s[6:7]
	v_fmac_f32_e32 v36, v0, v68
	v_mul_f32_e32 v0, v0, v67
	v_ashrrev_i32_e32 v67, 31, v66
	v_lshl_add_u64 v[34:35], v[66:67], 2, s[34:35]
	global_store_dword v[34:35], v0, off nt
	global_store_dword v[34:35], v36, off offset:2048 nt

; __device__ __forceinline__ bf16_t f2bf(float f) { unsigned u = __float_as_uint(f); u += 0x7FFFu + ((u >> 16) & 1u); return (bf16_t)(u >> 16); }
; template <int DIR>
; __device__ __forceinline__ void scan_dir(PP p, const bf16_t* xs, const ScanW& w, ScanW& wn, int ndir, int nct, bool do_next, int n, int ct, int l31, int hl, int id, int rowbase, bool latent, float (&hf)[2][16]) {
;     ...
;     float Sin[8], Pin[8]; float Sx = 0.f, Px = 1.f;
; #pragma unroll
;     for (int kk = 0; kk < 8; ++kk) {
;         const int k = DIR ? 7 - kk : kk;
;         const float A0 = hl ? Ap[k] : Ao[k], H0 = hl ? Hp[k] : Ho[k], A1 = hl ? Ao[k] : Ap[k], H1 = hl ? Ho[k] : Hp[k];
;         float s0, p0, s1, p1;
;         if (DIR == 0) { s0 = Sx; p0 = Px; Sx = A0 * Sx + H0; Px *= A0; s1 = Sx; p1 = Px; Sx = A1 * Sx + H1; Px *= A1; }
;         else          { s1 = Sx; p1 = Px; Sx = A1 * Sx + H1; Px *= A1; s0 = Sx; p0 = Px; Sx = A0 * Sx + H0; Px *= A0; }
;         Sin[k] = hl ? s1 : s0; Pin[k] = hl ? p1 : p0;
;     }
;     asm volatile("" ::: "memory");
;     if (do_next) scan_loadw(p, ndir, n, nct, l31, hl, wn);
;     bf16_t* yl = (bf16_t*)(p->ws + WS_YL) + (size_t)rowbase * 512; bf16_t* caf = (bf16_t*)(p->ws + WS_CAF) + (size_t)rowbase * 512; bf16_t* cab = (bf16_t*)(p->ws + WS_CAB) + (size_t)rowbase * 512;
;     unsigned lo = (unsigned)ch; asm volatile("" : "+v"(lo));
; #pragma unroll
;     for (int k = 0; k < 8; ++k) {
;         const int rt = k >> 2, g = k & 3;
;         float h = Sin[k], P = Pin[k];
; #pragma unroll
;         for (int jj = 0; jj < 4; ++jj) {
;             const int j = DIR ? 3 - jj : jj, idx = 4 * g + j;
;             h = a[rt][idx] * h + u[rt][idx]; P *= a[rt][idx];
;             const int token = 32 * rt + 8 * g + 4 * hl + j;
;             const unsigned o = lo + (unsigned)token * 512u;
;             if (DIR == 0) { hf[rt][idx] = h; if (latent) caf[o] = f2bf(P); }
;             else if (latent) { yl[o] = f2bf(hf[rt][idx] + h); cab[o] = f2bf(P); }
;         }
;     }
.LBB0_447:
	s_waitcnt lgkmcnt(0)
	v_cndmask_b32_e64 v0, v237, v158, s[6:7]
	v_cndmask_b32_e64 v238, v156, v220, s[6:7]
	v_cndmask_b32_e64 v158, v158, v237, s[6:7]
	v_cndmask_b32_e64 v159, v220, v156, s[6:7]
	v_fmac_f32_e32 v158, 0, v238
	v_fmac_f32_e32 v0, v159, v158
	v_mul_f32_e32 v156, v156, v220
	v_cndmask_b32_e64 v159, v235, v234, s[6:7]
	v_cndmask_b32_e64 v237, v236, v233, s[6:7]
	v_cndmask_b32_e64 v234, v234, v235, s[6:7]
	v_cndmask_b32_e64 v233, v233, v236, s[6:7]
	v_fmac_f32_e32 v233, v234, v0
	v_mul_f32_e32 v234, v234, v156
	v_fmac_f32_e32 v237, v159, v233
	v_mul_f32_e32 v235, v159, v234
	v_cndmask_b32_e64 v159, v231, v230, s[6:7]
	v_cndmask_b32_e64 v236, v232, v229, s[6:7]
	v_cndmask_b32_e64 v230, v230, v231, s[6:7]
	v_cndmask_b32_e64 v229, v229, v232, s[6:7]
	v_fmac_f32_e32 v229, v230, v237
	v_mul_f32_e32 v230, v230, v235
	v_fmac_f32_e32 v236, v159, v229
	v_mul_f32_e32 v231, v159, v230
	v_cndmask_b32_e64 v238, v227, v226, s[6:7]
	v_cndmask_b32_e64 v226, v226, v227, s[6:7]
	v_cndmask_b32_e64 v159, v225, v228, s[6:7]
	v_cndmask_b32_e64 v232, v228, v225, s[6:7]
	v_fmac_f32_e32 v159, v226, v236
	v_mul_f32_e32 v225, v226, v231
	v_fmac_f32_e32 v232, v238, v159
	v_mul_f32_e32 v226, v238, v225
	v_cndmask_b32_e64 v228, v223, v222, s[6:7]
	v_cndmask_b32_e64 v227, v224, v221, s[6:7]
	v_cndmask_b32_e64 v222, v222, v223, s[6:7]
	v_cndmask_b32_e64 v221, v221, v224, s[6:7]
	v_fmac_f32_e32 v221, v222, v232
	v_mul_f32_e32 v222, v222, v226
	v_fmac_f32_e32 v227, v228, v221
	v_mul_f32_e32 v223, v228, v222
	v_cndmask_b32_e64 v228, v218, v217, s[6:7]
	v_cndmask_b32_e64 v217, v217, v218, s[6:7]
	v_cndmask_b32_e64 v218, v216, v219, s[6:7]
	v_cndmask_b32_e64 v224, v219, v216, s[6:7]
	v_fmac_f32_e32 v218, v217, v227
	v_mul_f32_e32 v219, v217, v223
	v_fmac_f32_e32 v224, v228, v218
	v_mul_f32_e32 v228, v228, v219
	v_cndmask_b32_e64 v216, v212, v155, s[6:7]
	v_cndmask_b32_e64 v238, v215, v154, s[6:7]
	v_cndmask_b32_e64 v155, v155, v212, s[6:7]
	v_cndmask_b32_e64 v154, v154, v215, s[6:7]
	v_fmac_f32_e32 v154, v155, v224
	v_mul_f32_e32 v155, v155, v228
	v_fmac_f32_e32 v238, v216, v154
	v_mul_f32_e32 v212, v216, v155
	v_cndmask_b32_e64 v216, v78, v79, s[6:7]
	v_cndmask_b32_e64 v215, v65, v80, s[6:7]
	v_fmac_f32_e32 v215, v216, v238
	v_mul_f32_e32 v216, v216, v212
	v_mov_b32_e32 v217, v146
	s_andn2_b64 vcc, exec, s[22:23]
	s_cbranch_vccnz .LBB0_449
	v_cndmask_b32_e64 v233, v0, v233, s[6:7]
	v_cndmask_b32_e64 v0, v238, v215, s[6:7]
	v_cndmask_b32_e64 v219, v223, v219, s[6:7]
	v_cndmask_b32_e64 v223, v224, v154, s[6:7]
	v_cndmask_b32_e64 v154, v212, v216, s[6:7]
	v_fmac_f32_e32 v199, v198, v0
	v_mul_f32_e32 v212, v198, v154
	v_or_b32_e32 v0, 0x600, v153
	v_add_f32_e32 v154, v5, v199
	v_cndmask_b32_e64 v224, v228, v155, s[6:7]
	v_add_u32_e32 v0, v217, v0
	v_bfe_u32 v155, v154, 16, 1
	v_add3_u32 v198, v154, v155, s77
	v_lshlrev_b64 v[154:155], 1, v[0:1]
	v_bfe_u32 v0, v212, 16, 1
	v_cndmask_b32_e64 v239, 0, v158, s[6:7]
	v_cndmask_b32_e64 v156, v156, v234, s[6:7]
	v_cndmask_b32_e64 v234, v236, v159, s[6:7]
	v_lshl_add_u64 v[158:159], s[36:37], 0, v[154:155]
	v_add3_u32 v0, v212, v0, s77
	v_lshl_add_u64 v[154:155], s[38:39], 0, v[154:155]
	v_fmac_f32_e32 v197, v196, v199
	global_store_short_d16_hi v[154:155], v0, off nt
	v_or_b32_e32 v0, 0x400, v153
	v_add_f32_e32 v154, v4, v197
	global_store_short_d16_hi v[158:159], v198, off nt
	v_mul_f32_e32 v198, v196, v212
	v_add_u32_e32 v0, v217, v0
	v_bfe_u32 v155, v154, 16, 1
	v_add3_u32 v196, v154, v155, s77
	v_lshlrev_b64 v[154:155], 1, v[0:1]
	v_bfe_u32 v0, v198, 16, 1
	v_lshl_add_u64 v[158:159], s[36:37], 0, v[154:155]
	v_add3_u32 v0, v198, v0, s77
	v_lshl_add_u64 v[154:155], s[38:39], 0, v[154:155]
	v_fmac_f32_e32 v195, v147, v197
	global_store_short_d16_hi v[154:155], v0, off nt
	v_or_b32_e32 v0, 0x200, v153
	v_add_f32_e32 v154, v3, v195
	v_mul_f32_e32 v147, v147, v198
	v_add_u32_e32 v0, v217, v0
	v_bfe_u32 v155, v154, 16, 1
	global_store_short_d16_hi v[158:159], v196, off nt
	v_add3_u32 v196, v154, v155, s77
	v_lshlrev_b64 v[154:155], 1, v[0:1]
	v_bfe_u32 v0, v147, 16, 1
	v_fmac_f32_e32 v35, v34, v195
	v_lshl_add_u64 v[158:159], s[36:37], 0, v[154:155]
	v_add3_u32 v0, v147, v0, s77
	v_lshl_add_u64 v[154:155], s[38:39], 0, v[154:155]
	v_mul_f32_e32 v147, v34, v147
	v_add_f32_e32 v34, v2, v35
	global_store_short_d16_hi v[154:155], v0, off nt
	v_add_u32_e32 v0, v217, v153
	v_bfe_u32 v35, v34, 16, 1
	global_store_short_d16_hi v[158:159], v196, off nt
	v_add3_u32 v158, v34, v35, s77
	v_lshlrev_b64 v[34:35], 1, v[0:1]
	v_bfe_u32 v0, v147, 16, 1
	v_lshl_add_u64 v[154:155], s[36:37], 0, v[34:35]
	v_add3_u32 v0, v147, v0, s77
	v_lshl_add_u64 v[34:35], s[38:39], 0, v[34:35]
	v_fmac_f32_e32 v203, v202, v223
	global_store_short_d16_hi v[34:35], v0, off nt
	v_add_f32_e32 v34, v9, v203
	v_mul_f32_e32 v147, v202, v224
	v_add_u32_e32 v0, v217, v160
	v_bfe_u32 v35, v34, 16, 1
	global_store_short_d16_hi v[154:155], v158, off nt
	v_add3_u32 v158, v34, v35, s77
	v_lshlrev_b64 v[34:35], 1, v[0:1]
	v_bfe_u32 v0, v147, 16, 1
	v_lshl_add_u64 v[154:155], s[36:37], 0, v[34:35]
	v_add3_u32 v0, v147, v0, s77
	v_lshl_add_u64 v[34:35], s[38:39], 0, v[34:35]
	v_fmac_f32_e32 v201, v200, v203
	global_store_short_d16_hi v[34:35], v0, off nt
	v_or_b32_e32 v0, 0x1400, v153
	v_add_f32_e32 v34, v8, v201
	v_mul_f32_e32 v147, v200, v147
	v_add_u32_e32 v0, v217, v0
	v_bfe_u32 v35, v34, 16, 1
	global_store_short_d16_hi v[154:155], v158, off nt
	v_add3_u32 v158, v34, v35, s77
	v_lshlrev_b64 v[34:35], 1, v[0:1]
	v_bfe_u32 v0, v147, 16, 1
	v_lshl_add_u64 v[154:155], s[36:37], 0, v[34:35]
	v_add3_u32 v0, v147, v0, s77
	v_lshl_add_u64 v[34:35], s[38:39], 0, v[34:35]
; __device__ __forceinline__ bf16_t f2bf(float f) { unsigned u = __float_as_uint(f); u += 0x7FFFu + ((u >> 16) & 1u); return (bf16_t)(u >> 16); }
; template <int DIR>
; __device__ __forceinline__ void scan_dir(PP p, const bf16_t* xs, const ScanW& w, ScanW& wn, int ndir, int nct, bool do_next, int n, int ct, int l31, int hl, int id, int rowbase, bool latent, float (&hf)[2][16]) {
;     ...
;     for (int k = 0; k < 8; ++k) {
;         const int rt = k >> 2, g = k & 3;
;         float h = Sin[k], P = Pin[k];
; #pragma unroll
;         for (int jj = 0; jj < 4; ++jj) {
;             const int j = DIR ? 3 - jj : jj, idx = 4 * g + j;
;             h = a[rt][idx] * h + u[rt][idx]; P *= a[rt][idx];
;             const int token = 32 * rt + 8 * g + 4 * hl + j;
;             const unsigned o = lo + (unsigned)token * 512u;
;             if (DIR == 0) { hf[rt][idx] = h; if (latent) caf[o] = f2bf(P); }
;             else if (latent) { yl[o] = f2bf(hf[rt][idx] + h); cab[o] = f2bf(P); }
;         }
;     }
	v_fmac_f32_e32 v39, v38, v201
	global_store_short_d16_hi v[34:35], v0, off nt
	v_or_b32_e32 v0, 0x1200, v153
	v_add_f32_e32 v34, v7, v39
	v_mul_f32_e32 v38, v38, v147
	v_add_u32_e32 v0, v217, v0
	v_bfe_u32 v35, v34, 16, 1
	v_add3_u32 v147, v34, v35, s77
	v_lshlrev_b64 v[34:35], 1, v[0:1]
	v_bfe_u32 v0, v38, 16, 1
	global_store_short_d16_hi v[154:155], v158, off nt
	v_lshl_add_u64 v[154:155], s[36:37], 0, v[34:35]
	v_add3_u32 v0, v38, v0, s77
	v_lshl_add_u64 v[34:35], s[38:39], 0, v[34:35]
	v_fmac_f32_e32 v37, v36, v39
	global_store_short_d16_hi v[34:35], v0, off nt
	v_add_f32_e32 v34, v6, v37
	v_mul_f32_e32 v38, v36, v38
	v_add_u32_e32 v0, v217, v157
	v_bfe_u32 v35, v34, 16, 1
	v_cndmask_b32_e64 v218, v227, v218, s[6:7]
	v_add3_u32 v39, v34, v35, s77
	v_lshlrev_b64 v[34:35], 1, v[0:1]
	v_bfe_u32 v0, v38, 16, 1
	v_lshl_add_u64 v[36:37], s[36:37], 0, v[34:35]
	v_add3_u32 v0, v38, v0, s77
	v_lshl_add_u64 v[34:35], s[38:39], 0, v[34:35]
	v_fmac_f32_e32 v211, v205, v218
	global_store_short_d16_hi v[154:155], v147, off nt
	global_store_short_d16_hi v[34:35], v0, off nt
	v_add_f32_e32 v34, v13, v211
	v_mul_f32_e32 v38, v205, v219
	v_add_u32_e32 v0, v217, v164
	v_bfe_u32 v35, v34, 16, 1
	global_store_short_d16_hi v[36:37], v39, off nt
	v_add3_u32 v39, v34, v35, s77
	v_lshlrev_b64 v[34:35], 1, v[0:1]
	v_bfe_u32 v0, v38, 16, 1
	v_lshl_add_u64 v[36:37], s[36:37], 0, v[34:35]
	v_add3_u32 v0, v38, v0, s77
	v_lshl_add_u64 v[34:35], s[38:39], 0, v[34:35]
	v_fmac_f32_e32 v208, v204, v211
	global_store_short_d16_hi v[34:35], v0, off nt
	v_add_f32_e32 v34, v12, v208
	v_mul_f32_e32 v38, v204, v38
	v_add_u32_e32 v0, v217, v163
	v_bfe_u32 v35, v34, 16, 1
	global_store_short_d16_hi v[36:37], v39, off nt
	v_add3_u32 v39, v34, v35, s77
	v_lshlrev_b64 v[34:35], 1, v[0:1]
	v_bfe_u32 v0, v38, 16, 1
	v_lshl_add_u64 v[36:37], s[36:37], 0, v[34:35]
	v_add3_u32 v0, v38, v0, s77
	v_lshl_add_u64 v[34:35], s[38:39], 0, v[34:35]
	v_fmac_f32_e32 v43, v42, v208
	global_store_short_d16_hi v[34:35], v0, off nt
	v_add_f32_e32 v34, v11, v43
	v_mul_f32_e32 v38, v42, v38
	v_add_u32_e32 v0, v217, v162
	v_bfe_u32 v35, v34, 16, 1
	global_store_short_d16_hi v[36:37], v39, off nt
	v_add3_u32 v39, v34, v35, s77
	v_lshlrev_b64 v[34:35], 1, v[0:1]
	v_bfe_u32 v0, v38, 16, 1
	v_lshl_add_u64 v[36:37], s[36:37], 0, v[34:35]
	v_add3_u32 v0, v38, v0, s77
	v_lshl_add_u64 v[34:35], s[38:39], 0, v[34:35]
	v_fmac_f32_e32 v41, v40, v43
	global_store_short_d16_hi v[34:35], v0, off nt
	v_add_f32_e32 v34, v10, v41
	v_mul_f32_e32 v38, v40, v38
	v_add_u32_e32 v0, v217, v161
	v_bfe_u32 v35, v34, 16, 1
	v_cndmask_b32_e64 v221, v232, v221, s[6:7]
	global_store_short_d16_hi v[36:37], v39, off nt
	v_add3_u32 v39, v34, v35, s77
	v_lshlrev_b64 v[34:35], 1, v[0:1]
	v_bfe_u32 v0, v38, 16, 1
	v_lshl_add_u64 v[36:37], s[36:37], 0, v[34:35]
	v_add3_u32 v0, v38, v0, s77
	v_lshl_add_u64 v[34:35], s[38:39], 0, v[34:35]
	v_fmac_f32_e32 v210, v207, v221
	v_cndmask_b32_e64 v222, v226, v222, s[6:7]
	global_store_short_d16_hi v[34:35], v0, off nt
	v_add_f32_e32 v34, v17, v210
	v_mul_f32_e32 v38, v207, v222
	v_add_u32_e32 v0, v217, v168
	v_bfe_u32 v35, v34, 16, 1
	global_store_short_d16_hi v[36:37], v39, off nt
	v_add3_u32 v39, v34, v35, s77
	v_lshlrev_b64 v[34:35], 1, v[0:1]
	v_bfe_u32 v0, v38, 16, 1
	v_lshl_add_u64 v[36:37], s[36:37], 0, v[34:35]
	v_add3_u32 v0, v38, v0, s77
	v_lshl_add_u64 v[34:35], s[38:39], 0, v[34:35]
	v_fmac_f32_e32 v209, v206, v210
	global_store_short_d16_hi v[34:35], v0, off nt
	v_add_f32_e32 v34, v16, v209
	v_mul_f32_e32 v38, v206, v38
	v_add_u32_e32 v0, v217, v167
	v_bfe_u32 v35, v34, 16, 1
	global_store_short_d16_hi v[36:37], v39, off nt
	v_add3_u32 v39, v34, v35, s77
	v_lshlrev_b64 v[34:35], 1, v[0:1]
	v_bfe_u32 v0, v38, 16, 1
	v_lshl_add_u64 v[36:37], s[36:37], 0, v[34:35]
	v_add3_u32 v0, v38, v0, s77
	v_lshl_add_u64 v[34:35], s[38:39], 0, v[34:35]
	v_fmac_f32_e32 v48, v45, v209
	global_store_short_d16_hi v[34:35], v0, off nt
	v_add_f32_e32 v34, v15, v48
	v_mul_f32_e32 v38, v45, v38
	v_add_u32_e32 v0, v217, v166
	v_bfe_u32 v35, v34, 16, 1
	global_store_short_d16_hi v[36:37], v39, off nt
	v_add3_u32 v39, v34, v35, s77
	v_lshlrev_b64 v[34:35], 1, v[0:1]
	v_bfe_u32 v0, v38, 16, 1
	v_lshl_add_u64 v[36:37], s[36:37], 0, v[34:35]
	v_add3_u32 v0, v38, v0, s77
	v_lshl_add_u64 v[34:35], s[38:39], 0, v[34:35]
	v_fmac_f32_e32 v47, v44, v48
	global_store_short_d16_hi v[34:35], v0, off nt
	v_add_f32_e32 v34, v14, v47
	v_mul_f32_e32 v38, v44, v38
	v_add_u32_e32 v0, v217, v165
	v_bfe_u32 v35, v34, 16, 1
	global_store_short_d16_hi v[36:37], v39, off nt
	v_add3_u32 v39, v34, v35, s77
	v_lshlrev_b64 v[34:35], 1, v[0:1]
	v_bfe_u32 v0, v38, 16, 1
	v_lshl_add_u64 v[36:37], s[36:37], 0, v[34:35]
	v_add3_u32 v0, v38, v0, s77
	v_lshl_add_u64 v[34:35], s[38:39], 0, v[34:35]
	v_fmac_f32_e32 v69, v68, v234
	v_cndmask_b32_e64 v225, v231, v225, s[6:7]
	global_store_short_d16_hi v[34:35], v0, off nt
	v_add_f32_e32 v34, v21, v69
	v_mul_f32_e32 v38, v68, v225
	v_add_u32_e32 v0, v217, v172
	v_bfe_u32 v35, v34, 16, 1
	global_store_short_d16_hi v[36:37], v39, off nt
	v_add3_u32 v39, v34, v35, s77
	v_lshlrev_b64 v[34:35], 1, v[0:1]
	v_bfe_u32 v0, v38, 16, 1
	v_lshl_add_u64 v[36:37], s[36:37], 0, v[34:35]
	v_add3_u32 v0, v38, v0, s77
	v_lshl_add_u64 v[34:35], s[38:39], 0, v[34:35]
	v_fmac_f32_e32 v67, v66, v69
	global_store_short_d16_hi v[34:35], v0, off nt
	v_add_f32_e32 v34, v20, v67
	v_mul_f32_e32 v38, v66, v38
	v_add_u32_e32 v0, v217, v171
	v_bfe_u32 v35, v34, 16, 1
	global_store_short_d16_hi v[36:37], v39, off nt
	v_add3_u32 v39, v34, v35, s77
	v_lshlrev_b64 v[34:35], 1, v[0:1]
	v_bfe_u32 v0, v38, 16, 1
; __device__ __forceinline__ bf16_t f2bf(float f) { unsigned u = __float_as_uint(f); u += 0x7FFFu + ((u >> 16) & 1u); return (bf16_t)(u >> 16); }
; template <int DIR>
; __device__ __forceinline__ void scan_dir(PP p, const bf16_t* xs, const ScanW& w, ScanW& wn, int ndir, int nct, bool do_next, int n, int ct, int l31, int hl, int id, int rowbase, bool latent, float (&hf)[2][16]) {
;     ...
;     for (int k = 0; k < 8; ++k) {
;         const int rt = k >> 2, g = k & 3;
;         float h = Sin[k], P = Pin[k];
; #pragma unroll
;         for (int jj = 0; jj < 4; ++jj) {
;             const int j = DIR ? 3 - jj : jj, idx = 4 * g + j;
;             h = a[rt][idx] * h + u[rt][idx]; P *= a[rt][idx];
;             const int token = 32 * rt + 8 * g + 4 * hl + j;
;             const unsigned o = lo + (unsigned)token * 512u;
;             if (DIR == 0) { hf[rt][idx] = h; if (latent) caf[o] = f2bf(P); }
;             else if (latent) { yl[o] = f2bf(hf[rt][idx] + h); cab[o] = f2bf(P); }
;         }
;     }
	v_lshl_add_u64 v[36:37], s[36:37], 0, v[34:35]
	v_add3_u32 v0, v38, v0, s77
	v_lshl_add_u64 v[34:35], s[38:39], 0, v[34:35]
	v_fmac_f32_e32 v51, v50, v67
	global_store_short_d16_hi v[34:35], v0, off nt
	v_add_f32_e32 v34, v19, v51
	v_mul_f32_e32 v38, v50, v38
	v_add_u32_e32 v0, v217, v170
	v_bfe_u32 v35, v34, 16, 1
	global_store_short_d16_hi v[36:37], v39, off nt
	v_add3_u32 v39, v34, v35, s77
	v_lshlrev_b64 v[34:35], 1, v[0:1]
	v_bfe_u32 v0, v38, 16, 1
	v_lshl_add_u64 v[36:37], s[36:37], 0, v[34:35]
	v_add3_u32 v0, v38, v0, s77
	v_lshl_add_u64 v[34:35], s[38:39], 0, v[34:35]
	v_fmac_f32_e32 v49, v46, v51
	global_store_short_d16_hi v[34:35], v0, off nt
	v_add_f32_e32 v34, v18, v49
	v_mul_f32_e32 v38, v46, v38
	v_add_u32_e32 v0, v217, v169
	v_bfe_u32 v35, v34, 16, 1
	v_cndmask_b32_e64 v229, v237, v229, s[6:7]
	global_store_short_d16_hi v[36:37], v39, off nt
	v_add3_u32 v39, v34, v35, s77
	v_lshlrev_b64 v[34:35], 1, v[0:1]
	v_bfe_u32 v0, v38, 16, 1
	v_lshl_add_u64 v[36:37], s[36:37], 0, v[34:35]
	v_add3_u32 v0, v38, v0, s77
	v_lshl_add_u64 v[34:35], s[38:39], 0, v[34:35]
	v_fmac_f32_e32 v73, v72, v229
	v_cndmask_b32_e64 v230, v235, v230, s[6:7]
	global_store_short_d16_hi v[34:35], v0, off nt
	v_add_f32_e32 v34, v25, v73
	v_mul_f32_e32 v38, v72, v230
	v_add_u32_e32 v0, v217, v176
	v_bfe_u32 v35, v34, 16, 1
	global_store_short_d16_hi v[36:37], v39, off nt
	v_add3_u32 v39, v34, v35, s77
	v_lshlrev_b64 v[34:35], 1, v[0:1]
	v_bfe_u32 v0, v38, 16, 1
	v_lshl_add_u64 v[36:37], s[36:37], 0, v[34:35]
	v_add3_u32 v0, v38, v0, s77
	v_lshl_add_u64 v[34:35], s[38:39], 0, v[34:35]
	v_fmac_f32_e32 v71, v70, v73
	global_store_short_d16_hi v[34:35], v0, off nt
	v_add_f32_e32 v34, v24, v71
	v_mul_f32_e32 v38, v70, v38
	v_add_u32_e32 v0, v217, v175
	v_bfe_u32 v35, v34, 16, 1
	global_store_short_d16_hi v[36:37], v39, off nt
	v_add3_u32 v39, v34, v35, s77
	v_lshlrev_b64 v[34:35], 1, v[0:1]
	v_bfe_u32 v0, v38, 16, 1
	v_lshl_add_u64 v[36:37], s[36:37], 0, v[34:35]
	v_add3_u32 v0, v38, v0, s77
	v_lshl_add_u64 v[34:35], s[38:39], 0, v[34:35]
	v_fmac_f32_e32 v55, v54, v71
	global_store_short_d16_hi v[34:35], v0, off nt
	v_add_f32_e32 v34, v23, v55
	v_mul_f32_e32 v38, v54, v38
	v_add_u32_e32 v0, v217, v174
	v_bfe_u32 v35, v34, 16, 1
	global_store_short_d16_hi v[36:37], v39, off nt
	v_add3_u32 v39, v34, v35, s77
	v_lshlrev_b64 v[34:35], 1, v[0:1]
	v_bfe_u32 v0, v38, 16, 1
	v_lshl_add_u64 v[36:37], s[36:37], 0, v[34:35]
	v_add3_u32 v0, v38, v0, s77
	v_lshl_add_u64 v[34:35], s[38:39], 0, v[34:35]
	v_fmac_f32_e32 v53, v52, v55
	global_store_short_d16_hi v[34:35], v0, off nt
	v_add_f32_e32 v34, v22, v53
	v_mul_f32_e32 v38, v52, v38
	v_add_u32_e32 v0, v217, v173
	v_bfe_u32 v35, v34, 16, 1
	global_store_short_d16_hi v[36:37], v39, off nt
	v_add3_u32 v39, v34, v35, s77
	v_lshlrev_b64 v[34:35], 1, v[0:1]
	v_bfe_u32 v0, v38, 16, 1
	v_lshl_add_u64 v[36:37], s[36:37], 0, v[34:35]
	v_add3_u32 v0, v38, v0, s77
	v_lshl_add_u64 v[34:35], s[38:39], 0, v[34:35]
	v_fmac_f32_e32 v77, v76, v233
	global_store_short_d16_hi v[34:35], v0, off nt
	v_add_f32_e32 v34, v29, v77
	v_mul_f32_e32 v38, v76, v156
	v_add_u32_e32 v0, v217, v180
	v_bfe_u32 v35, v34, 16, 1
	global_store_short_d16_hi v[36:37], v39, off nt
	v_add3_u32 v39, v34, v35, s77
	v_lshlrev_b64 v[34:35], 1, v[0:1]
	v_bfe_u32 v0, v38, 16, 1
	v_lshl_add_u64 v[36:37], s[36:37], 0, v[34:35]
	v_add3_u32 v0, v38, v0, s77
	v_lshl_add_u64 v[34:35], s[38:39], 0, v[34:35]
	v_fmac_f32_e32 v75, v74, v77
	global_store_short_d16_hi v[34:35], v0, off nt
	v_add_f32_e32 v34, v28, v75
	v_mul_f32_e32 v38, v74, v38
	v_add_u32_e32 v0, v217, v179
	v_bfe_u32 v35, v34, 16, 1
	global_store_short_d16_hi v[36:37], v39, off nt
	v_add3_u32 v39, v34, v35, s77
	v_lshlrev_b64 v[34:35], 1, v[0:1]
	v_bfe_u32 v0, v38, 16, 1
	v_lshl_add_u64 v[36:37], s[36:37], 0, v[34:35]
	v_add3_u32 v0, v38, v0, s77
	v_lshl_add_u64 v[34:35], s[38:39], 0, v[34:35]
	v_fmac_f32_e32 v59, v58, v75
	global_store_short_d16_hi v[34:35], v0, off nt
	v_add_f32_e32 v34, v27, v59
	v_mul_f32_e32 v38, v58, v38
	v_add_u32_e32 v0, v217, v178
	v_bfe_u32 v35, v34, 16, 1
	global_store_short_d16_hi v[36:37], v39, off nt
	v_add3_u32 v39, v34, v35, s77
	v_lshlrev_b64 v[34:35], 1, v[0:1]
	v_bfe_u32 v0, v38, 16, 1
	v_lshl_add_u64 v[36:37], s[36:37], 0, v[34:35]
	v_add3_u32 v0, v38, v0, s77
	v_lshl_add_u64 v[34:35], s[38:39], 0, v[34:35]
	v_fmac_f32_e32 v57, v56, v59
	global_store_short_d16_hi v[34:35], v0, off nt
	v_add_f32_e32 v34, v26, v57
	v_mul_f32_e32 v38, v56, v38
	v_add_u32_e32 v0, v217, v177
	v_bfe_u32 v35, v34, 16, 1
	global_store_short_d16_hi v[36:37], v39, off nt
	v_add3_u32 v39, v34, v35, s77
	v_lshlrev_b64 v[34:35], 1, v[0:1]
	v_bfe_u32 v0, v38, 16, 1
	v_lshl_add_u64 v[36:37], s[36:37], 0, v[34:35]
	v_add3_u32 v0, v38, v0, s77
	v_lshl_add_u64 v[34:35], s[38:39], 0, v[34:35]
	v_fmac_f32_e32 v214, v213, v239
	v_cndmask_b32_e64 v220, 1.0, v220, s[6:7]
	global_store_short_d16_hi v[34:35], v0, off nt
	v_add_f32_e32 v34, v33, v214
	v_mul_f32_e32 v38, v213, v220
	v_add_u32_e32 v0, v217, v184
	v_bfe_u32 v35, v34, 16, 1
	global_store_short_d16_hi v[36:37], v39, off nt
	v_add3_u32 v39, v34, v35, s77
	v_lshlrev_b64 v[34:35], 1, v[0:1]
	v_bfe_u32 v0, v38, 16, 1
	v_lshl_add_u64 v[36:37], s[36:37], 0, v[34:35]
	v_add3_u32 v0, v38, v0, s77
	v_lshl_add_u64 v[34:35], s[38:39], 0, v[34:35]
	v_fmac_f32_e32 v81, v64, v214
	global_store_short_d16_hi v[34:35], v0, off nt
	v_add_f32_e32 v34, v32, v81
	v_mul_f32_e32 v38, v64, v38
	v_add_u32_e32 v0, v217, v183
	v_bfe_u32 v35, v34, 16, 1
	global_store_short_d16_hi v[36:37], v39, off nt
	v_add3_u32 v39, v34, v35, s77
	v_lshlrev_b64 v[34:35], 1, v[0:1]
	v_bfe_u32 v0, v38, 16, 1
	v_lshl_add_u64 v[36:37], s[36:37], 0, v[34:35]
	v_add3_u32 v0, v38, v0, s77
	v_lshl_add_u64 v[34:35], s[38:39], 0, v[34:35]
	v_fmac_f32_e32 v63, v62, v81
	global_store_short_d16_hi v[34:35], v0, off nt
	v_add_f32_e32 v34, v31, v63
	v_mul_f32_e32 v38, v62, v38
	v_add_u32_e32 v0, v217, v182
	v_bfe_u32 v35, v34, 16, 1
	global_store_short_d16_hi v[36:37], v39, off nt
	v_add3_u32 v39, v34, v35, s77
	v_lshlrev_b64 v[34:35], 1, v[0:1]
	v_bfe_u32 v0, v38, 16, 1
	v_lshl_add_u64 v[36:37], s[36:37], 0, v[34:35]
	v_add3_u32 v0, v38, v0, s77
	v_lshl_add_u64 v[34:35], s[38:39], 0, v[34:35]
	v_fmac_f32_e32 v61, v60, v63
	global_store_short_d16_hi v[34:35], v0, off nt
	v_add_f32_e32 v34, v30, v61
	v_mul_f32_e32 v38, v60, v38
	v_add_u32_e32 v0, v217, v181
	v_bfe_u32 v35, v34, 16, 1
	global_store_short_d16_hi v[36:37], v39, off nt
	v_add3_u32 v39, v34, v35, s77
	v_lshlrev_b64 v[34:35], 1, v[0:1]
	v_bfe_u32 v0, v38, 16, 1
	v_lshl_add_u64 v[36:37], s[36:37], 0, v[34:35]
	v_add3_u32 v0, v38, v0, s77
	v_lshl_add_u64 v[34:35], s[38:39], 0, v[34:35]
	global_store_short_d16_hi v[36:37], v39, off nt
	global_store_short_d16_hi v[34:35], v0, off nt
